# p8: next unit's prepare loads (row stats + column sums) issued inside the epilogue into dead accumulator registers; plus zero64 + prep2
# speedup vs baseline: 1.0025x; 1.0025x over previous
; #define LAS __attribute__((address_space(3)))
; __device__ __forceinline__ float bf_lo(unsigned w) { return __uint_as_float(w << 16); }
;     __device__ __forceinline__ void operator()(const f32x4 (&acc)[2][2][4][2], const pg8::Unit& u, int wr, int wc, int fr, int fq, LAS unsigned char* lds, int par) const {
;         const bool fold = F.stats != nullptr;
;         const LAS float* rsb = (const LAS float*)(lds + RS_OFF) + par * 512; const LAS float* cvb = (const LAS float*)(lds + CV_OFF) + (par * 2 + wr) * 512;
;         const int row0 = u.pm * 256 + wr * 64 + fr, c0 = u.pn * 256 + wc * 64 + 16 * fq;
; #pragma unroll
;         for (int ai = 0; ai < 2; ++ai)
; #pragma unroll
;             for (int m = 0; m < 4; ++m) {
;                 const int row = row0 + ai * 128 + m * 16, lrow = ai * 128 + wr * 64 + m * 16 + fr;
;                 float mu = 0.f, rstd = 1.f; if (fold) { mu = rsb[2 * lrow]; rstd = rsb[2 * lrow + 1]; }
; #pragma unroll
;                 for (int bj = 0; bj < 2; ++bj) {
;                     const size_t off = (size_t)row * ld + c0 + bj * 8;
;                     f32x4 v0 = acc[ai][bj][m][0], v1 = acc[ai][bj][m][1];
;                     if (fold) fold_apply(v0, v1, mu, rstd, cvb, wc * 64 + 16 * fq + bj * 8);
;                     if (MODE == 0) { v0 *= scale; v1 *= scale; }
;                     if (MODE == 1) {
; #pragma unroll
;                         for (int j = 0; j < 4; ++j) { const float a = fmaxf(v0[j], 0.f), b = fmaxf(v1[j], 0.f); v0[j] = a * a; v1[j] = b * b; }
;                     }
;                     if (MODE == 2 || MODE == 3) {
;                         const u32x4 gw = *(const u32x4*)(gate + off);
;                         v0[0] *= bf_lo(gw.x); v0[1] *= bf_hi(gw.x); v0[2] *= bf_lo(gw.y); v0[3] *= bf_hi(gw.y);
;                         v1[0] *= bf_lo(gw.z); v1[1] *= bf_hi(gw.z); v1[2] *= bf_lo(gw.w); v1[3] *= bf_hi(gw.w);
;                     }
;                     if (MODE == 3) {
;                         const u32x4 pw = *(const u32x4*)(o + off);
;                         v0[0] += bf_lo(pw.x); v0[1] += bf_hi(pw.x); v0[2] += bf_lo(pw.y); v0[3] += bf_hi(pw.y);
;                         v1[0] += bf_lo(pw.z); v1[1] += bf_hi(pw.z); v1[2] += bf_lo(pw.w); v1[3] += bf_hi(pw.w);
;                     }
;                     *(u32x4*)(o + off) = pack8(v0, v1);
.LBB0_176:
	s_and_b32 s15, s41, 1
	v_lshl_add_u32 v156, s15, 12, v153
	v_lshl_add_u32 v157, s15, 11, v152
	v_readlane_b32 s26, v251, 43
	v_readlane_b32 s27, v251, 44
	ds_read_b128 v[212:215], v156
	ds_read_b128 v[216:219], v156 offset:16
	ds_read_b128 v[220:223], v156 offset:32
	ds_read_b128 v[224:227], v156 offset:48
	ds_read_b128 v[228:231], v156 offset:64
	ds_read_b128 v[232:235], v156 offset:80
	ds_read_b128 v[236:239], v156 offset:96
	ds_read_b128 v[240:243], v156 offset:112
	ds_read_b64 v[172:173], v157
	ds_read_b64 v[174:175], v157 offset:128
	ds_read_b64 v[176:177], v157 offset:256
	ds_read_b64 v[178:179], v157 offset:384
	ds_read_b64 v[180:181], v157 offset:1024
	ds_read_b64 v[182:183], v157 offset:1152
	ds_read_b64 v[184:185], v157 offset:1280
	ds_read_b64 v[186:187], v157 offset:1408
	v_lshl_add_u32 v158, s24, 8, v148
	v_lshl_or_b32 v159, s40, 8, v150
	v_lshlrev_b32_e32 v201, 14, v158
	v_lshl_add_u32 v201, v159, 1, v201
	s_waitcnt lgkmcnt(0)
	v_mul_f32_e32 v200, v173, v172
	v_mov_b32_e32 v155, v201
	v_fma_f32 v188, -v200, v212, v213
	v_fma_f32 v189, -v200, v214, v215
	v_fma_f32 v190, -v200, v216, v217
	v_fma_f32 v191, -v200, v218, v219
	v_fma_f32 v192, -v200, v220, v221
	v_fma_f32 v193, -v200, v222, v223
	v_fma_f32 v194, -v200, v224, v225
	v_fma_f32 v195, -v200, v226, v227
	v_fma_f32 v126, v173, v126, v188
	v_fma_f32 v127, v173, v127, v189
	v_fma_f32 v128, v173, v128, v190
	v_fma_f32 v129, v173, v129, v191
	v_fma_f32 v122, v173, v122, v192
	v_fma_f32 v123, v173, v123, v193
	v_fma_f32 v124, v173, v124, v194
	v_fma_f32 v125, v173, v125, v195
	v_max_f32_e32 v126, 0, v126
	v_max_f32_e32 v127, 0, v127
	v_max_f32_e32 v128, 0, v128
	v_max_f32_e32 v129, 0, v129
	v_max_f32_e32 v122, 0, v122
	v_max_f32_e32 v123, 0, v123
	v_max_f32_e32 v124, 0, v124
	v_max_f32_e32 v125, 0, v125
	v_mul_f32_e32 v126, v126, v126
	v_mul_f32_e32 v127, v127, v127
	v_mul_f32_e32 v128, v128, v128
	v_mul_f32_e32 v129, v129, v129
	v_mul_f32_e32 v122, v122, v122
	v_mul_f32_e32 v123, v123, v123
	v_mul_f32_e32 v124, v124, v124
	v_mul_f32_e32 v125, v125, v125
	v_cvt_pk_bf16_f32 v196, v126, v127
	v_cvt_pk_bf16_f32 v197, v128, v129
	v_cvt_pk_bf16_f32 v198, v122, v123
	v_cvt_pk_bf16_f32 v199, v124, v125
	global_store_dwordx4 v155, v[196:199], s[26:27]
	v_fma_f32 v188, -v200, v228, v229
	v_fma_f32 v189, -v200, v230, v231
	v_fma_f32 v190, -v200, v232, v233
	v_fma_f32 v191, -v200, v234, v235
	v_fma_f32 v192, -v200, v236, v237
	v_fma_f32 v193, -v200, v238, v239
	v_fma_f32 v194, -v200, v240, v241
	v_fma_f32 v195, -v200, v242, v243
	v_fma_f32 v118, v173, v118, v188
	v_fma_f32 v119, v173, v119, v189
	v_fma_f32 v120, v173, v120, v190
	v_fma_f32 v121, v173, v121, v191
	v_fma_f32 v114, v173, v114, v192
	v_fma_f32 v115, v173, v115, v193
	v_fma_f32 v116, v173, v116, v194
	v_fma_f32 v117, v173, v117, v195
	v_max_f32_e32 v118, 0, v118
	v_max_f32_e32 v119, 0, v119
	v_max_f32_e32 v120, 0, v120
	v_max_f32_e32 v121, 0, v121
	v_max_f32_e32 v114, 0, v114
	v_max_f32_e32 v115, 0, v115
	v_max_f32_e32 v116, 0, v116
	v_max_f32_e32 v117, 0, v117
	v_mul_f32_e32 v118, v118, v118
	v_mul_f32_e32 v119, v119, v119
	v_mul_f32_e32 v120, v120, v120
	v_mul_f32_e32 v121, v121, v121
	v_mul_f32_e32 v114, v114, v114
	v_mul_f32_e32 v115, v115, v115
	v_mul_f32_e32 v116, v116, v116
	v_mul_f32_e32 v117, v117, v117
	v_cvt_pk_bf16_f32 v196, v118, v119
	v_cvt_pk_bf16_f32 v197, v120, v121
	v_cvt_pk_bf16_f32 v198, v114, v115
	v_cvt_pk_bf16_f32 v199, v116, v117
	global_store_dwordx4 v155, v[196:199], s[26:27] offset:16
	v_mul_f32_e32 v200, v175, v174
	v_add_u32_e32 v155, 0x40000, v201
	v_fma_f32 v188, -v200, v212, v213
	v_fma_f32 v189, -v200, v214, v215
	v_fma_f32 v190, -v200, v216, v217
	v_fma_f32 v191, -v200, v218, v219
	v_fma_f32 v192, -v200, v220, v221
	v_fma_f32 v193, -v200, v222, v223
	v_fma_f32 v194, -v200, v224, v225
	v_fma_f32 v195, -v200, v226, v227
	v_fma_f32 v110, v175, v110, v188
	v_fma_f32 v111, v175, v111, v189
	v_fma_f32 v112, v175, v112, v190
	v_fma_f32 v113, v175, v113, v191
	v_fma_f32 v106, v175, v106, v192
	v_fma_f32 v107, v175, v107, v193
	v_fma_f32 v108, v175, v108, v194
	v_fma_f32 v109, v175, v109, v195
	v_max_f32_e32 v110, 0, v110
	v_max_f32_e32 v111, 0, v111
	v_max_f32_e32 v112, 0, v112
	v_max_f32_e32 v113, 0, v113
	v_max_f32_e32 v106, 0, v106
	v_max_f32_e32 v107, 0, v107
	v_max_f32_e32 v108, 0, v108
	v_max_f32_e32 v109, 0, v109
	v_mul_f32_e32 v110, v110, v110
	v_mul_f32_e32 v111, v111, v111
	v_mul_f32_e32 v112, v112, v112
	v_mul_f32_e32 v113, v113, v113
	v_mul_f32_e32 v106, v106, v106
	v_mul_f32_e32 v107, v107, v107
	v_mul_f32_e32 v108, v108, v108
	v_mul_f32_e32 v109, v109, v109
	v_cvt_pk_bf16_f32 v196, v110, v111
	v_cvt_pk_bf16_f32 v197, v112, v113
	v_cvt_pk_bf16_f32 v198, v106, v107
	v_cvt_pk_bf16_f32 v199, v108, v109
	global_store_dwordx4 v155, v[196:199], s[26:27]
	v_fma_f32 v188, -v200, v228, v229
	v_fma_f32 v189, -v200, v230, v231
	v_fma_f32 v190, -v200, v232, v233
	v_fma_f32 v191, -v200, v234, v235
	v_fma_f32 v192, -v200, v236, v237
	v_fma_f32 v193, -v200, v238, v239
	v_fma_f32 v194, -v200, v240, v241
	v_fma_f32 v195, -v200, v242, v243
	v_fma_f32 v102, v175, v102, v188
	v_fma_f32 v103, v175, v103, v189
	v_fma_f32 v104, v175, v104, v190
	v_fma_f32 v105, v175, v105, v191
	v_fma_f32 v98, v175, v98, v192
	v_fma_f32 v99, v175, v99, v193
	v_fma_f32 v100, v175, v100, v194
	v_fma_f32 v101, v175, v101, v195
	v_max_f32_e32 v102, 0, v102
	v_max_f32_e32 v103, 0, v103
	v_max_f32_e32 v104, 0, v104
	v_max_f32_e32 v105, 0, v105
	v_max_f32_e32 v98, 0, v98
	v_max_f32_e32 v99, 0, v99
	v_max_f32_e32 v100, 0, v100
	v_max_f32_e32 v101, 0, v101
	v_mul_f32_e32 v102, v102, v102
	v_mul_f32_e32 v103, v103, v103
;     __device__ __forceinline__ void prepare(const pg8::Unit& u, LAS unsigned char* lds, int par, int tid) const {
;         if (stats == nullptr) return;
;         const int h = tid >> 8, tt = tid & 255, rl = tt >> 1, part = tt & 1, lrow = (rl >> 6) * 128 + h * 64 + (rl & 63);
;         const float* sp = stats + ((size_t)(u.pm * 256 + lrow) * 32 + part * 16) * 2;
;         float s1 = 0.f, s2 = 0.f;
; #pragma unroll
;         for (int i = 0; i < 8; ++i) { const f32x4 v = *(const f32x4*)(sp + 4 * i); s1 += v[0] + v[2]; s2 += v[1] + v[3]; }
;         s1 += shflx(s1, 1, tid & 63); s2 += shflx(s2, 1, tid & 63);
;     __device__ __forceinline__ void operator()(const f32x4 (&acc)[2][2][4][2], const pg8::Unit& u, int wr, int wc, int fr, int fq, LAS unsigned char* lds, int par) const {
;     ...
;                 const int row = row0 + ai * 128 + m * 16, lrow = ai * 128 + wr * 64 + m * 16 + fr;
;                 float mu = 0.f, rstd = 1.f; if (fold) { mu = rsb[2 * lrow]; rstd = rsb[2 * lrow + 1]; }
; #pragma unroll
;                 for (int bj = 0; bj < 2; ++bj) {
;                     const size_t off = (size_t)row * ld + c0 + bj * 8;
;                     f32x4 v0 = acc[ai][bj][m][0], v1 = acc[ai][bj][m][1];
;                     if (fold) fold_apply(v0, v1, mu, rstd, cvb, wc * 64 + 16 * fq + bj * 8);
;                     if (MODE == 0) { v0 *= scale; v1 *= scale; }
;                     if (MODE == 1) {
; #pragma unroll
;                         for (int j = 0; j < 4; ++j) { const float a = fmaxf(v0[j], 0.f), b = fmaxf(v1[j], 0.f); v0[j] = a * a; v1[j] = b * b; }
;                     }
;                     if (MODE == 2 || MODE == 3) {
;                         const u32x4 gw = *(const u32x4*)(gate + off);
;                         v0[0] *= bf_lo(gw.x); v0[1] *= bf_hi(gw.x); v0[2] *= bf_lo(gw.y); v0[3] *= bf_hi(gw.y);
;                         v1[0] *= bf_lo(gw.z); v1[1] *= bf_hi(gw.z); v1[2] *= bf_lo(gw.w); v1[3] *= bf_hi(gw.w);
;                     }
;                     if (MODE == 3) {
;                         const u32x4 pw = *(const u32x4*)(o + off);
;                         v0[0] += bf_lo(pw.x); v0[1] += bf_hi(pw.x); v0[2] += bf_lo(pw.y); v0[3] += bf_hi(pw.y);
;                         v1[0] += bf_lo(pw.z); v1[1] += bf_hi(pw.z); v1[2] += bf_lo(pw.w); v1[3] += bf_hi(pw.w);
;                     }
;                     *(u32x4*)(o + off) = pack8(v0, v1);
	v_mul_f32_e32 v104, v104, v104
	v_mul_f32_e32 v105, v105, v105
	v_mul_f32_e32 v98, v98, v98
	v_mul_f32_e32 v99, v99, v99
	v_mul_f32_e32 v100, v100, v100
	v_mul_f32_e32 v101, v101, v101
	v_cvt_pk_bf16_f32 v196, v102, v103
	v_cvt_pk_bf16_f32 v197, v104, v105
	v_cvt_pk_bf16_f32 v198, v98, v99
	v_cvt_pk_bf16_f32 v199, v100, v101
	global_store_dwordx4 v155, v[196:199], s[26:27] offset:16
	v_mul_f32_e32 v200, v177, v176
	v_add_u32_e32 v155, 0x80000, v201
	v_fma_f32 v188, -v200, v212, v213
	v_fma_f32 v189, -v200, v214, v215
	v_fma_f32 v190, -v200, v216, v217
	v_fma_f32 v191, -v200, v218, v219
	v_fma_f32 v192, -v200, v220, v221
	v_fma_f32 v193, -v200, v222, v223
	v_fma_f32 v194, -v200, v224, v225
	v_fma_f32 v195, -v200, v226, v227
	v_fma_f32 v94, v177, v94, v188
	v_fma_f32 v95, v177, v95, v189
	v_fma_f32 v96, v177, v96, v190
	v_fma_f32 v97, v177, v97, v191
	v_fma_f32 v90, v177, v90, v192
	v_fma_f32 v91, v177, v91, v193
	v_fma_f32 v92, v177, v92, v194
	v_fma_f32 v93, v177, v93, v195
	v_max_f32_e32 v94, 0, v94
	v_max_f32_e32 v95, 0, v95
	v_max_f32_e32 v96, 0, v96
	v_max_f32_e32 v97, 0, v97
	v_max_f32_e32 v90, 0, v90
	v_max_f32_e32 v91, 0, v91
	v_max_f32_e32 v92, 0, v92
	v_max_f32_e32 v93, 0, v93
	v_mul_f32_e32 v94, v94, v94
	v_mul_f32_e32 v95, v95, v95
	v_mul_f32_e32 v96, v96, v96
	v_mul_f32_e32 v97, v97, v97
	v_mul_f32_e32 v90, v90, v90
	v_mul_f32_e32 v91, v91, v91
	v_mul_f32_e32 v92, v92, v92
	v_mul_f32_e32 v93, v93, v93
	v_cvt_pk_bf16_f32 v196, v94, v95
	v_cvt_pk_bf16_f32 v197, v96, v97
	v_cvt_pk_bf16_f32 v198, v90, v91
	v_cvt_pk_bf16_f32 v199, v92, v93
	global_store_dwordx4 v155, v[196:199], s[26:27]
	v_fma_f32 v188, -v200, v228, v229
	v_fma_f32 v189, -v200, v230, v231
	v_fma_f32 v190, -v200, v232, v233
	v_fma_f32 v191, -v200, v234, v235
	v_fma_f32 v192, -v200, v236, v237
	v_fma_f32 v193, -v200, v238, v239
	v_fma_f32 v194, -v200, v240, v241
	v_fma_f32 v195, -v200, v242, v243
	v_fma_f32 v86, v177, v86, v188
	v_fma_f32 v87, v177, v87, v189
	v_fma_f32 v88, v177, v88, v190
	v_fma_f32 v89, v177, v89, v191
	v_fma_f32 v82, v177, v82, v192
	v_fma_f32 v83, v177, v83, v193
	v_fma_f32 v84, v177, v84, v194
	v_fma_f32 v85, v177, v85, v195
	v_max_f32_e32 v86, 0, v86
	v_max_f32_e32 v87, 0, v87
	v_max_f32_e32 v88, 0, v88
	v_max_f32_e32 v89, 0, v89
	v_max_f32_e32 v82, 0, v82
	v_max_f32_e32 v83, 0, v83
	v_max_f32_e32 v84, 0, v84
	v_max_f32_e32 v85, 0, v85
	v_mul_f32_e32 v86, v86, v86
	v_mul_f32_e32 v87, v87, v87
	v_mul_f32_e32 v88, v88, v88
	v_mul_f32_e32 v89, v89, v89
	v_mul_f32_e32 v82, v82, v82
	v_mul_f32_e32 v83, v83, v83
	v_mul_f32_e32 v84, v84, v84
	v_mul_f32_e32 v85, v85, v85
	v_cvt_pk_bf16_f32 v196, v86, v87
	v_cvt_pk_bf16_f32 v197, v88, v89
	v_cvt_pk_bf16_f32 v198, v82, v83
	v_cvt_pk_bf16_f32 v199, v84, v85
	global_store_dwordx4 v155, v[196:199], s[26:27] offset:16
	s_and_b64 vcc, exec, s[22:23]
	s_cbranch_vccz .Lprep3_skip
	v_lshl_add_u32 v160, s16, 8, v144
	v_ashrrev_i32_e32 v161, 31, v160
	v_lshlrev_b64 v[160:161], 8, v[160:161]
	v_lshl_add_u64 v[162:163], v[136:137], 0, v[160:161]
	v_lshl_or_b32 v164, s14, 8, v146
	v_lshlrev_b32_e32 v164, 2, v164
	global_load_dwordx4 v[126:129], v[162:163], off
	global_load_dwordx4 v[122:125], v[162:163], off offset:16
	global_load_dwordx4 v[118:121], v[162:163], off offset:32
	global_load_dwordx4 v[114:117], v[162:163], off offset:48
	global_load_dwordx4 v[110:113], v[162:163], off offset:64
	global_load_dwordx4 v[106:109], v[162:163], off offset:80
	global_load_dwordx4 v[102:105], v[162:163], off offset:96
	global_load_dwordx4 v[98:101], v[162:163], off offset:112
	v_add_u32_e32 v96, 0x8000, v164
	v_add_u32_e32 v90, 0x10000, v164
	v_add_u32_e32 v92, 0x18000, v164
	v_add_u32_e32 v95, 0x20000, v164
	v_add_u32_e32 v97, 0x28000, v164
	v_add_u32_e32 v91, 0x30000, v164
	v_add_u32_e32 v93, 0x38000, v164
	global_load_dword v94, v164, s[4:5]
	global_load_dword v96, v96, s[4:5]
	global_load_dword v90, v90, s[4:5]
	global_load_dword v92, v92, s[4:5]
	global_load_dword v95, v95, s[4:5]
	global_load_dword v97, v97, s[4:5]
	global_load_dword v91, v91, s[4:5]
	global_load_dword v93, v93, s[4:5]
.Lprep3_skip:
	v_mul_f32_e32 v200, v179, v178
	v_add_u32_e32 v155, 0xc0000, v201
	v_fma_f32 v188, -v200, v212, v213
	v_fma_f32 v189, -v200, v214, v215
	v_fma_f32 v190, -v200, v216, v217
	v_fma_f32 v191, -v200, v218, v219
	v_fma_f32 v192, -v200, v220, v221
	v_fma_f32 v193, -v200, v222, v223
	v_fma_f32 v194, -v200, v224, v225
	v_fma_f32 v195, -v200, v226, v227
	v_fma_f32 v78, v179, v78, v188
	v_fma_f32 v79, v179, v79, v189
	v_fma_f32 v80, v179, v80, v190
	v_fma_f32 v81, v179, v81, v191
	v_fma_f32 v74, v179, v74, v192
	v_fma_f32 v75, v179, v75, v193
	v_fma_f32 v76, v179, v76, v194
	v_fma_f32 v77, v179, v77, v195
	v_max_f32_e32 v78, 0, v78
	v_max_f32_e32 v79, 0, v79
	v_max_f32_e32 v80, 0, v80
	v_max_f32_e32 v81, 0, v81
	v_max_f32_e32 v74, 0, v74
	v_max_f32_e32 v75, 0, v75
	v_max_f32_e32 v76, 0, v76
	v_max_f32_e32 v77, 0, v77
	v_mul_f32_e32 v78, v78, v78
	v_mul_f32_e32 v79, v79, v79
	v_mul_f32_e32 v80, v80, v80
	v_mul_f32_e32 v81, v81, v81
	v_mul_f32_e32 v74, v74, v74
	v_mul_f32_e32 v75, v75, v75
	v_mul_f32_e32 v76, v76, v76
	v_mul_f32_e32 v77, v77, v77
	v_cvt_pk_bf16_f32 v196, v78, v79
	v_cvt_pk_bf16_f32 v197, v80, v81
	v_cvt_pk_bf16_f32 v198, v74, v75
	v_cvt_pk_bf16_f32 v199, v76, v77
	global_store_dwordx4 v155, v[196:199], s[26:27]
	v_fma_f32 v188, -v200, v228, v229
	v_fma_f32 v189, -v200, v230, v231
	v_fma_f32 v190, -v200, v232, v233
	v_fma_f32 v191, -v200, v234, v235
	v_fma_f32 v192, -v200, v236, v237
	v_fma_f32 v193, -v200, v238, v239
	v_fma_f32 v194, -v200, v240, v241
	v_fma_f32 v195, -v200, v242, v243
	v_fma_f32 v70, v179, v70, v188
; __device__ __forceinline__ float bf_lo(unsigned w) { return __uint_as_float(w << 16); }
; __device__ __forceinline__ float bf_hi(unsigned w) { return __uint_as_float(w & 0xffff0000u); }
; __device__ __forceinline__ u32x4 pack8(const f32x4 a, const f32x4 b) { u32x4 w; w.x = cvt_pk_bf16(a[0], a[1]); w.y = cvt_pk_bf16(a[2], a[3]); w.z = cvt_pk_bf16(b[0], b[1]); w.w = cvt_pk_bf16(b[2], b[3]); return w; }
;     __device__ __forceinline__ void operator()(const f32x4 (&acc)[2][2][4][2], const pg8::Unit& u, int wr, int wc, int fr, int fq, LAS unsigned char* lds, int par) const {
;     ...
;                 const int row = row0 + ai * 128 + m * 16, lrow = ai * 128 + wr * 64 + m * 16 + fr;
;                 float mu = 0.f, rstd = 1.f; if (fold) { mu = rsb[2 * lrow]; rstd = rsb[2 * lrow + 1]; }
; #pragma unroll
;                 for (int bj = 0; bj < 2; ++bj) {
;                     const size_t off = (size_t)row * ld + c0 + bj * 8;
;                     f32x4 v0 = acc[ai][bj][m][0], v1 = acc[ai][bj][m][1];
;                     if (fold) fold_apply(v0, v1, mu, rstd, cvb, wc * 64 + 16 * fq + bj * 8);
;                     if (MODE == 0) { v0 *= scale; v1 *= scale; }
;                     if (MODE == 1) {
; #pragma unroll
;                         for (int j = 0; j < 4; ++j) { const float a = fmaxf(v0[j], 0.f), b = fmaxf(v1[j], 0.f); v0[j] = a * a; v1[j] = b * b; }
;                     }
;                     if (MODE == 2 || MODE == 3) {
;                         const u32x4 gw = *(const u32x4*)(gate + off);
;                         v0[0] *= bf_lo(gw.x); v0[1] *= bf_hi(gw.x); v0[2] *= bf_lo(gw.y); v0[3] *= bf_hi(gw.y);
;                         v1[0] *= bf_lo(gw.z); v1[1] *= bf_hi(gw.z); v1[2] *= bf_lo(gw.w); v1[3] *= bf_hi(gw.w);
;                     }
;                     if (MODE == 3) {
;                         const u32x4 pw = *(const u32x4*)(o + off);
;                         v0[0] += bf_lo(pw.x); v0[1] += bf_hi(pw.x); v0[2] += bf_lo(pw.y); v0[3] += bf_hi(pw.y);
;                         v1[0] += bf_lo(pw.z); v1[1] += bf_hi(pw.z); v1[2] += bf_lo(pw.w); v1[3] += bf_hi(pw.w);
;                     }
;                     *(u32x4*)(o + off) = pack8(v0, v1);
	v_fma_f32 v71, v179, v71, v189
	v_fma_f32 v72, v179, v72, v190
	v_fma_f32 v73, v179, v73, v191
	v_fma_f32 v66, v179, v66, v192
	v_fma_f32 v67, v179, v67, v193
	v_fma_f32 v68, v179, v68, v194
	v_fma_f32 v69, v179, v69, v195
	v_max_f32_e32 v70, 0, v70
	v_max_f32_e32 v71, 0, v71
	v_max_f32_e32 v72, 0, v72
	v_max_f32_e32 v73, 0, v73
	v_max_f32_e32 v66, 0, v66
	v_max_f32_e32 v67, 0, v67
	v_max_f32_e32 v68, 0, v68
	v_max_f32_e32 v69, 0, v69
	v_mul_f32_e32 v70, v70, v70
	v_mul_f32_e32 v71, v71, v71
	v_mul_f32_e32 v72, v72, v72
	v_mul_f32_e32 v73, v73, v73
	v_mul_f32_e32 v66, v66, v66
	v_mul_f32_e32 v67, v67, v67
	v_mul_f32_e32 v68, v68, v68
	v_mul_f32_e32 v69, v69, v69
	v_cvt_pk_bf16_f32 v196, v70, v71
	v_cvt_pk_bf16_f32 v197, v72, v73
	v_cvt_pk_bf16_f32 v198, v66, v67
	v_cvt_pk_bf16_f32 v199, v68, v69
	global_store_dwordx4 v155, v[196:199], s[26:27] offset:16
	v_mul_f32_e32 v200, v181, v180
	v_add_u32_e32 v155, 0x200000, v201
	v_fma_f32 v188, -v200, v212, v213
	v_fma_f32 v189, -v200, v214, v215
	v_fma_f32 v190, -v200, v216, v217
	v_fma_f32 v191, -v200, v218, v219
	v_fma_f32 v192, -v200, v220, v221
	v_fma_f32 v193, -v200, v222, v223
	v_fma_f32 v194, -v200, v224, v225
	v_fma_f32 v195, -v200, v226, v227
	v_fma_f32 v62, v181, v62, v188
	v_fma_f32 v63, v181, v63, v189
	v_fma_f32 v64, v181, v64, v190
	v_fma_f32 v65, v181, v65, v191
	v_fma_f32 v58, v181, v58, v192
	v_fma_f32 v59, v181, v59, v193
	v_fma_f32 v60, v181, v60, v194
	v_fma_f32 v61, v181, v61, v195
	v_max_f32_e32 v62, 0, v62
	v_max_f32_e32 v63, 0, v63
	v_max_f32_e32 v64, 0, v64
	v_max_f32_e32 v65, 0, v65
	v_max_f32_e32 v58, 0, v58
	v_max_f32_e32 v59, 0, v59
	v_max_f32_e32 v60, 0, v60
	v_max_f32_e32 v61, 0, v61
	v_mul_f32_e32 v62, v62, v62
	v_mul_f32_e32 v63, v63, v63
	v_mul_f32_e32 v64, v64, v64
	v_mul_f32_e32 v65, v65, v65
	v_mul_f32_e32 v58, v58, v58
	v_mul_f32_e32 v59, v59, v59
	v_mul_f32_e32 v60, v60, v60
	v_mul_f32_e32 v61, v61, v61
	v_cvt_pk_bf16_f32 v196, v62, v63
	v_cvt_pk_bf16_f32 v197, v64, v65
	v_cvt_pk_bf16_f32 v198, v58, v59
	v_cvt_pk_bf16_f32 v199, v60, v61
	global_store_dwordx4 v155, v[196:199], s[26:27]
	v_fma_f32 v188, -v200, v228, v229
	v_fma_f32 v189, -v200, v230, v231
	v_fma_f32 v190, -v200, v232, v233
	v_fma_f32 v191, -v200, v234, v235
	v_fma_f32 v192, -v200, v236, v237
	v_fma_f32 v193, -v200, v238, v239
	v_fma_f32 v194, -v200, v240, v241
	v_fma_f32 v195, -v200, v242, v243
	v_fma_f32 v54, v181, v54, v188
	v_fma_f32 v55, v181, v55, v189
	v_fma_f32 v56, v181, v56, v190
	v_fma_f32 v57, v181, v57, v191
	v_fma_f32 v50, v181, v50, v192
	v_fma_f32 v51, v181, v51, v193
	v_fma_f32 v52, v181, v52, v194
	v_fma_f32 v53, v181, v53, v195
	v_max_f32_e32 v54, 0, v54
	v_max_f32_e32 v55, 0, v55
	v_max_f32_e32 v56, 0, v56
	v_max_f32_e32 v57, 0, v57
	v_max_f32_e32 v50, 0, v50
	v_max_f32_e32 v51, 0, v51
	v_max_f32_e32 v52, 0, v52
	v_max_f32_e32 v53, 0, v53
	v_mul_f32_e32 v54, v54, v54
	v_mul_f32_e32 v55, v55, v55
	v_mul_f32_e32 v56, v56, v56
	v_mul_f32_e32 v57, v57, v57
	v_mul_f32_e32 v50, v50, v50
	v_mul_f32_e32 v51, v51, v51
	v_mul_f32_e32 v52, v52, v52
	v_mul_f32_e32 v53, v53, v53
	v_cvt_pk_bf16_f32 v196, v54, v55
	v_cvt_pk_bf16_f32 v197, v56, v57
	v_cvt_pk_bf16_f32 v198, v50, v51
	v_cvt_pk_bf16_f32 v199, v52, v53
	global_store_dwordx4 v155, v[196:199], s[26:27] offset:16
	v_mul_f32_e32 v200, v183, v182
	v_add_u32_e32 v155, 0x240000, v201
	v_fma_f32 v188, -v200, v212, v213
	v_fma_f32 v189, -v200, v214, v215
	v_fma_f32 v190, -v200, v216, v217
	v_fma_f32 v191, -v200, v218, v219
	v_fma_f32 v192, -v200, v220, v221
	v_fma_f32 v193, -v200, v222, v223
	v_fma_f32 v194, -v200, v224, v225
	v_fma_f32 v195, -v200, v226, v227
	v_fma_f32 v46, v183, v46, v188
	v_fma_f32 v47, v183, v47, v189
	v_fma_f32 v48, v183, v48, v190
	v_fma_f32 v49, v183, v49, v191
	v_fma_f32 v42, v183, v42, v192
	v_fma_f32 v43, v183, v43, v193
	v_fma_f32 v44, v183, v44, v194
	v_fma_f32 v45, v183, v45, v195
	v_max_f32_e32 v46, 0, v46
	v_max_f32_e32 v47, 0, v47
	v_max_f32_e32 v48, 0, v48
	v_max_f32_e32 v49, 0, v49
	v_max_f32_e32 v42, 0, v42
	v_max_f32_e32 v43, 0, v43
	v_max_f32_e32 v44, 0, v44
	v_max_f32_e32 v45, 0, v45
	v_mul_f32_e32 v46, v46, v46
	v_mul_f32_e32 v47, v47, v47
	v_mul_f32_e32 v48, v48, v48
	v_mul_f32_e32 v49, v49, v49
	v_mul_f32_e32 v42, v42, v42
	v_mul_f32_e32 v43, v43, v43
	v_mul_f32_e32 v44, v44, v44
	v_mul_f32_e32 v45, v45, v45
	v_cvt_pk_bf16_f32 v196, v46, v47
	v_cvt_pk_bf16_f32 v197, v48, v49
	v_cvt_pk_bf16_f32 v198, v42, v43
	v_cvt_pk_bf16_f32 v199, v44, v45
	global_store_dwordx4 v155, v[196:199], s[26:27]
	v_fma_f32 v188, -v200, v228, v229
	v_fma_f32 v189, -v200, v230, v231
	v_fma_f32 v190, -v200, v232, v233
	v_fma_f32 v191, -v200, v234, v235
	v_fma_f32 v192, -v200, v236, v237
	v_fma_f32 v193, -v200, v238, v239
	v_fma_f32 v194, -v200, v240, v241
	v_fma_f32 v195, -v200, v242, v243
	v_fma_f32 v38, v183, v38, v188
	v_fma_f32 v39, v183, v39, v189
	v_fma_f32 v40, v183, v40, v190
	v_fma_f32 v41, v183, v41, v191
	v_fma_f32 v34, v183, v34, v192
	v_fma_f32 v35, v183, v35, v193
	v_fma_f32 v36, v183, v36, v194
	v_fma_f32 v37, v183, v37, v195
	v_max_f32_e32 v38, 0, v38
	v_max_f32_e32 v39, 0, v39
	v_max_f32_e32 v40, 0, v40
	v_max_f32_e32 v41, 0, v41
	v_max_f32_e32 v34, 0, v34
	v_max_f32_e32 v35, 0, v35
	v_max_f32_e32 v36, 0, v36
	v_max_f32_e32 v37, 0, v37
	v_mul_f32_e32 v38, v38, v38
	v_mul_f32_e32 v39, v39, v39
	v_mul_f32_e32 v40, v40, v40
	v_mul_f32_e32 v41, v41, v41
	v_mul_f32_e32 v34, v34, v34
	v_mul_f32_e32 v35, v35, v35
	v_mul_f32_e32 v36, v36, v36
	v_mul_f32_e32 v37, v37, v37
	v_cvt_pk_bf16_f32 v196, v38, v39
	v_cvt_pk_bf16_f32 v197, v40, v41
	v_cvt_pk_bf16_f32 v198, v34, v35
	v_cvt_pk_bf16_f32 v199, v36, v37
;     __device__ __forceinline__ void prepare(const pg8::Unit& u, LAS unsigned char* lds, int par, int tid) const {
;         if (stats == nullptr) return;
;         const int h = tid >> 8, tt = tid & 255, rl = tt >> 1, part = tt & 1, lrow = (rl >> 6) * 128 + h * 64 + (rl & 63);
;         const float* sp = stats + ((size_t)(u.pm * 256 + lrow) * 32 + part * 16) * 2;
;         float s1 = 0.f, s2 = 0.f;
; #pragma unroll
;         for (int i = 0; i < 8; ++i) { const f32x4 v = *(const f32x4*)(sp + 4 * i); s1 += v[0] + v[2]; s2 += v[1] + v[3]; }
;         s1 += shflx(s1, 1, tid & 63); s2 += shflx(s2, 1, tid & 63);
;     __device__ __forceinline__ void operator()(const f32x4 (&acc)[2][2][4][2], const pg8::Unit& u, int wr, int wc, int fr, int fq, LAS unsigned char* lds, int par) const {
;     ...
;                 const int row = row0 + ai * 128 + m * 16, lrow = ai * 128 + wr * 64 + m * 16 + fr;
;                 float mu = 0.f, rstd = 1.f; if (fold) { mu = rsb[2 * lrow]; rstd = rsb[2 * lrow + 1]; }
; #pragma unroll
;                 for (int bj = 0; bj < 2; ++bj) {
;                     const size_t off = (size_t)row * ld + c0 + bj * 8;
;                     f32x4 v0 = acc[ai][bj][m][0], v1 = acc[ai][bj][m][1];
;                     if (fold) fold_apply(v0, v1, mu, rstd, cvb, wc * 64 + 16 * fq + bj * 8);
;                     if (MODE == 0) { v0 *= scale; v1 *= scale; }
;                     if (MODE == 1) {
; #pragma unroll
;                         for (int j = 0; j < 4; ++j) { const float a = fmaxf(v0[j], 0.f), b = fmaxf(v1[j], 0.f); v0[j] = a * a; v1[j] = b * b; }
;                     }
;                     if (MODE == 2 || MODE == 3) {
;                         const u32x4 gw = *(const u32x4*)(gate + off);
;                         v0[0] *= bf_lo(gw.x); v0[1] *= bf_hi(gw.x); v0[2] *= bf_lo(gw.y); v0[3] *= bf_hi(gw.y);
;                         v1[0] *= bf_lo(gw.z); v1[1] *= bf_hi(gw.z); v1[2] *= bf_lo(gw.w); v1[3] *= bf_hi(gw.w);
;                     }
;                     if (MODE == 3) {
;                         const u32x4 pw = *(const u32x4*)(o + off);
;                         v0[0] += bf_lo(pw.x); v0[1] += bf_hi(pw.x); v0[2] += bf_lo(pw.y); v0[3] += bf_hi(pw.y);
;                         v1[0] += bf_lo(pw.z); v1[1] += bf_hi(pw.z); v1[2] += bf_lo(pw.w); v1[3] += bf_hi(pw.w);
;                     }
;                     *(u32x4*)(o + off) = pack8(v0, v1);
	global_store_dwordx4 v155, v[196:199], s[26:27] offset:16
	v_mul_f32_e32 v200, v185, v184
	v_add_u32_e32 v155, 0x280000, v201
	v_fma_f32 v188, -v200, v212, v213
	v_fma_f32 v189, -v200, v214, v215
	v_fma_f32 v190, -v200, v216, v217
	v_fma_f32 v191, -v200, v218, v219
	v_fma_f32 v192, -v200, v220, v221
	v_fma_f32 v193, -v200, v222, v223
	v_fma_f32 v194, -v200, v224, v225
	v_fma_f32 v195, -v200, v226, v227
	v_fma_f32 v30, v185, v30, v188
	v_fma_f32 v31, v185, v31, v189
	v_fma_f32 v32, v185, v32, v190
	v_fma_f32 v33, v185, v33, v191
	v_fma_f32 v26, v185, v26, v192
	v_fma_f32 v27, v185, v27, v193
	v_fma_f32 v28, v185, v28, v194
	v_fma_f32 v29, v185, v29, v195
	v_max_f32_e32 v30, 0, v30
	v_max_f32_e32 v31, 0, v31
	v_max_f32_e32 v32, 0, v32
	v_max_f32_e32 v33, 0, v33
	v_max_f32_e32 v26, 0, v26
	v_max_f32_e32 v27, 0, v27
	v_max_f32_e32 v28, 0, v28
	v_max_f32_e32 v29, 0, v29
	v_mul_f32_e32 v30, v30, v30
	v_mul_f32_e32 v31, v31, v31
	v_mul_f32_e32 v32, v32, v32
	v_mul_f32_e32 v33, v33, v33
	v_mul_f32_e32 v26, v26, v26
	v_mul_f32_e32 v27, v27, v27
	v_mul_f32_e32 v28, v28, v28
	v_mul_f32_e32 v29, v29, v29
	v_cvt_pk_bf16_f32 v196, v30, v31
	v_cvt_pk_bf16_f32 v197, v32, v33
	v_cvt_pk_bf16_f32 v198, v26, v27
	v_cvt_pk_bf16_f32 v199, v28, v29
	global_store_dwordx4 v155, v[196:199], s[26:27]
	v_fma_f32 v188, -v200, v228, v229
	v_fma_f32 v189, -v200, v230, v231
	v_fma_f32 v190, -v200, v232, v233
	v_fma_f32 v191, -v200, v234, v235
	v_fma_f32 v192, -v200, v236, v237
	v_fma_f32 v193, -v200, v238, v239
	v_fma_f32 v194, -v200, v240, v241
	v_fma_f32 v195, -v200, v242, v243
	v_fma_f32 v22, v185, v22, v188
	v_fma_f32 v23, v185, v23, v189
	v_fma_f32 v24, v185, v24, v190
	v_fma_f32 v25, v185, v25, v191
	v_fma_f32 v18, v185, v18, v192
	v_fma_f32 v19, v185, v19, v193
	v_fma_f32 v20, v185, v20, v194
	v_fma_f32 v21, v185, v21, v195
	v_max_f32_e32 v22, 0, v22
	v_max_f32_e32 v23, 0, v23
	v_max_f32_e32 v24, 0, v24
	v_max_f32_e32 v25, 0, v25
	v_max_f32_e32 v18, 0, v18
	v_max_f32_e32 v19, 0, v19
	v_max_f32_e32 v20, 0, v20
	v_max_f32_e32 v21, 0, v21
	v_mul_f32_e32 v22, v22, v22
	v_mul_f32_e32 v23, v23, v23
	v_mul_f32_e32 v24, v24, v24
	v_mul_f32_e32 v25, v25, v25
	v_mul_f32_e32 v18, v18, v18
	v_mul_f32_e32 v19, v19, v19
	v_mul_f32_e32 v20, v20, v20
	v_mul_f32_e32 v21, v21, v21
	v_cvt_pk_bf16_f32 v196, v22, v23
	v_cvt_pk_bf16_f32 v197, v24, v25
	v_cvt_pk_bf16_f32 v198, v18, v19
	v_cvt_pk_bf16_f32 v199, v20, v21
	global_store_dwordx4 v155, v[196:199], s[26:27] offset:16
	v_mul_f32_e32 v200, v187, v186
	v_add_u32_e32 v155, 0x2c0000, v201
	v_fma_f32 v188, -v200, v212, v213
	v_fma_f32 v189, -v200, v214, v215
	v_fma_f32 v190, -v200, v216, v217
	v_fma_f32 v191, -v200, v218, v219
	v_fma_f32 v192, -v200, v220, v221
	v_fma_f32 v193, -v200, v222, v223
	v_fma_f32 v194, -v200, v224, v225
	v_fma_f32 v195, -v200, v226, v227
	v_fma_f32 v14, v187, v14, v188
	v_fma_f32 v15, v187, v15, v189
	v_fma_f32 v16, v187, v16, v190
	v_fma_f32 v17, v187, v17, v191
	v_fma_f32 v10, v187, v10, v192
	v_fma_f32 v11, v187, v11, v193
	v_fma_f32 v12, v187, v12, v194
	v_fma_f32 v13, v187, v13, v195
	v_max_f32_e32 v14, 0, v14
	v_max_f32_e32 v15, 0, v15
	v_max_f32_e32 v16, 0, v16
	v_max_f32_e32 v17, 0, v17
	v_max_f32_e32 v10, 0, v10
	v_max_f32_e32 v11, 0, v11
	v_max_f32_e32 v12, 0, v12
	v_max_f32_e32 v13, 0, v13
	v_mul_f32_e32 v14, v14, v14
	v_mul_f32_e32 v15, v15, v15
	v_mul_f32_e32 v16, v16, v16
	v_mul_f32_e32 v17, v17, v17
	v_mul_f32_e32 v10, v10, v10
	v_mul_f32_e32 v11, v11, v11
	v_mul_f32_e32 v12, v12, v12
	v_mul_f32_e32 v13, v13, v13
	v_cvt_pk_bf16_f32 v196, v14, v15
	v_cvt_pk_bf16_f32 v197, v16, v17
	v_cvt_pk_bf16_f32 v198, v10, v11
	v_cvt_pk_bf16_f32 v199, v12, v13
	global_store_dwordx4 v155, v[196:199], s[26:27]
	v_fma_f32 v188, -v200, v228, v229
	v_fma_f32 v189, -v200, v230, v231
	v_fma_f32 v190, -v200, v232, v233
	v_fma_f32 v191, -v200, v234, v235
	v_fma_f32 v192, -v200, v236, v237
	v_fma_f32 v193, -v200, v238, v239
	v_fma_f32 v194, -v200, v240, v241
	v_fma_f32 v195, -v200, v242, v243
	v_fma_f32 v6, v187, v6, v188
	v_fma_f32 v7, v187, v7, v189
	v_fma_f32 v8, v187, v8, v190
	v_fma_f32 v9, v187, v9, v191
	v_fma_f32 v2, v187, v2, v192
	v_fma_f32 v3, v187, v3, v193
	v_fma_f32 v4, v187, v4, v194
	v_fma_f32 v5, v187, v5, v195
	v_max_f32_e32 v6, 0, v6
	v_max_f32_e32 v7, 0, v7
	v_max_f32_e32 v8, 0, v8
	v_max_f32_e32 v9, 0, v9
	v_max_f32_e32 v2, 0, v2
	v_max_f32_e32 v3, 0, v3
	v_max_f32_e32 v4, 0, v4
	v_max_f32_e32 v5, 0, v5
	v_mul_f32_e32 v6, v6, v6
	v_mul_f32_e32 v7, v7, v7
	v_mul_f32_e32 v8, v8, v8
	v_mul_f32_e32 v9, v9, v9
	v_mul_f32_e32 v2, v2, v2
	v_mul_f32_e32 v3, v3, v3
	v_mul_f32_e32 v4, v4, v4
	v_mul_f32_e32 v5, v5, v5
	v_cvt_pk_bf16_f32 v196, v6, v7
	v_cvt_pk_bf16_f32 v197, v8, v9
	v_cvt_pk_bf16_f32 v198, v2, v3
	v_cvt_pk_bf16_f32 v199, v4, v5
	global_store_dwordx4 v155, v[196:199], s[26:27] offset:16
	s_andn2_b64 vcc, exec, s[22:23]
	s_mov_b64 s[22:23], -1
	s_cbranch_vccnz .LBB0_164
	s_nop 0
	s_and_b32 s15, s39, 1
	s_waitcnt vmcnt(0) lgkmcnt(0)
	v_add_f32_e32 v2, v126, v128
	v_add_f32_e32 v8, 0, v2
	v_add_f32_e32 v2, v127, v129
	v_add_f32_e32 v9, 0, v2
	v_add_f32_e32 v2, v122, v124
	v_add_f32_e32 v8, v8, v2
	v_add_f32_e32 v2, v123, v125
	v_add_f32_e32 v9, v9, v2
	v_add_f32_e32 v2, v118, v120
	v_add_f32_e32 v8, v8, v2
	v_add_f32_e32 v2, v119, v121
	v_add_f32_e32 v9, v9, v2
	v_add_f32_e32 v2, v114, v116
	v_add_f32_e32 v8, v8, v2
	v_add_f32_e32 v2, v115, v117
	v_add_f32_e32 v9, v9, v2
	v_add_f32_e32 v2, v110, v112
	v_add_f32_e32 v8, v8, v2
	v_add_f32_e32 v2, v111, v113
	v_add_f32_e32 v9, v9, v2
	v_add_f32_e32 v2, v106, v108
	v_add_f32_e32 v8, v8, v2
	v_add_f32_e32 v2, v107, v109
	v_add_f32_e32 v9, v9, v2
	v_add_f32_e32 v2, v102, v104
	v_add_f32_e32 v8, v8, v2
	v_add_f32_e32 v2, v103, v105
	v_add_f32_e32 v9, v9, v2
	v_add_f32_e32 v2, v98, v100
	v_add_f32_e32 v3, v99, v101
	v_add_f32_e32 v2, v8, v2
	v_add_f32_e32 v3, v9, v3
	ds_bpermute_b32 v4, v145, v2
	ds_bpermute_b32 v5, v145, v3
	s_and_saveexec_b64 s[22:23], s[0:1]
	s_cbranch_execz .LBB0_179
	s_waitcnt lgkmcnt(1)
	v_add_f32_e32 v2, v2, v4
	v_mul_f32_e32 v2, 0x3a000000, v2
	s_waitcnt lgkmcnt(0)
	v_add_f32_e32 v3, v3, v5
	v_mul_f32_e32 v4, v2, v2
	v_fma_f32 v3, v3, s61, -v4
	v_add_f32_e32 v3, 0x3727c5ac, v3
	v_rsq_f32_e32 v3, v3
	v_lshl_add_u32 v4, s15, 11, v151
	ds_write_b64 v4, v[2:3]
.LBB0_179:
	s_or_b64 exec, exec, s[22:23]
	s_waitcnt lgkmcnt(0)
	v_lshl_add_u32 v12, s15, 12, v147
	s_andn2_b64 vcc, exec, s[6:7]
	v_pk_add_f32 v[2:3], v[94:95], v[96:97]
	v_pk_add_f32 v[4:5], v[90:91], v[92:93]
	s_nop 0
	v_pk_add_f32 v[2:3], v[2:3], v[4:5]
	ds_write_b64 v12, v[2:3]
	s_cbranch_vccnz .LBB0_163
	s_barrier
	s_branch .LBB0_163
